# chunk-prep step 4 MFMA block and step 6 U/W tiles: LDS operand reads batched ahead with counted lgkmcnt, two independent MFMA chains interleaved (on top of branch-free step-4 epilogues)
# speedup vs baseline: 1.0109x; 1.0019x over previous
.LBB0_136:
	s_cmp_lt_u32 s48, 4
	s_cselect_b32 s7, s6, s52
	v_lshl_or_b32 v2, s7, 5, v94
	v_mul_u32_u24_e32 v2, 0x110, v2
	v_lshlrev_b32_e32 v6, 4, v95
	v_add3_u32 v26, s91, v2, v6
	s_cselect_b32 s7, s52, s6
	v_lshl_or_b32 v7, s7, 5, v94
	s_cselect_b32 s8, s91, s49
	v_mul_u32_u24_e32 v7, 0x110, v7
	v_add3_u32 v27, s8, v7, v6
	ds_read_b128 v[18:21], v26
	ds_read_b128 v[22:25], v27
	ds_read_b128 v[106:109], v26 offset:32
	ds_read_b128 v[110:113], v27 offset:32
	ds_read_b128 v[114:117], v26 offset:64
	ds_read_b128 v[118:121], v27 offset:64
	ds_read_b128 v[122:125], v26 offset:96
	ds_read_b128 v[126:129], v27 offset:96
	s_waitcnt lgkmcnt(6)
	v_mfma_f32_32x32x16_bf16 v[2:17], v[18:21], v[22:25], 0
	ds_read_b128 v[18:21], v26 offset:128
	ds_read_b128 v[22:25], v27 offset:128
	s_waitcnt lgkmcnt(6)
	v_mfma_f32_32x32x16_bf16 v[2:17], v[106:109], v[110:113], v[2:17]
	ds_read_b128 v[106:109], v26 offset:160
	ds_read_b128 v[110:113], v27 offset:160
	s_waitcnt lgkmcnt(6)
	v_mfma_f32_32x32x16_bf16 v[2:17], v[114:117], v[118:121], v[2:17]
	ds_read_b128 v[114:117], v26 offset:192
	ds_read_b128 v[118:121], v27 offset:192
	s_waitcnt lgkmcnt(6)
	v_mfma_f32_32x32x16_bf16 v[2:17], v[122:125], v[126:129], v[2:17]
	ds_read_b128 v[122:125], v26 offset:224
	ds_read_b128 v[126:129], v27 offset:224
	s_waitcnt lgkmcnt(6)
	v_mfma_f32_32x32x16_bf16 v[2:17], v[18:21], v[22:25], v[2:17]
	s_waitcnt lgkmcnt(4)
	v_mfma_f32_32x32x16_bf16 v[2:17], v[106:109], v[110:113], v[2:17]
	s_waitcnt lgkmcnt(2)
	v_mfma_f32_32x32x16_bf16 v[2:17], v[114:117], v[118:121], v[2:17]
	s_waitcnt lgkmcnt(0)
	v_mfma_f32_32x32x16_bf16 v[2:17], v[122:125], v[126:129], v[2:17]
	s_cmp_gt_u32 s48, 3
	v_lshlrev_b32_e32 v25, 2, v95
	s_mov_b64 s[28:29], -1
	s_cbranch_scc0 .LBB0_135

.LBB0_239:
	s_lshl_b32 s6, s53, 12
	v_lshlrev_b32_e32 v1, 3, v1
	s_add_i32 s6, s6, 0
	s_add_i32 s7, s6, 0x10000
	v_and_b32_e32 v1, 56, v1
	v_lshlrev_b32_e32 v89, 7, v94
	v_xor_b32_e32 v90, v88, v1
	v_xor_b32_e32 v91, v18, v1
	v_add_u32_e32 v89, s7, v89
	v_mul_u32_u24_e32 v1, 0x90, v96
	v_lshl_add_u32 v1, v88, 1, v1
	v_add_u32_e32 v1, s49, v1
	v_lshl_add_u32 v88, v90, 1, v89
	v_xor_b32_e32 v18, 32, v90
	v_xor_b32_e32 v90, 48, v90
	v_lshl_add_u32 v91, v91, 1, v89
	v_lshl_add_u32 v90, v90, 1, v89
	v_lshl_add_u32 v89, v18, 1, v89
	s_waitcnt lgkmcnt(0)
	s_barrier
	ds_read_b128 v[18:21], v1
	ds_read_b128 v[22:25], v88
	ds_read_b128 v[26:29], v88 offset:16384
	ds_read_b128 v[30:33], v1 offset:9216
	ds_read_b128 v[122:125], v1 offset:32
	ds_read_b128 v[126:129], v91
	s_add_i32 s7, s51, 0xe000
	s_mov_b64 s[40:41], 0
	s_waitcnt lgkmcnt(4)
	v_mfma_f32_32x32x16_bf16 v[2:17], v[18:21], v[22:25], 0
	ds_read_b128 v[18:21], v91 offset:16384
	ds_read_b128 v[22:25], v1 offset:9248
	s_waitcnt lgkmcnt(4)
	v_mfma_f32_32x32x16_bf16 v[106:121], v[26:29], v[30:33], 0
	ds_read_b128 v[26:29], v1 offset:64
	ds_read_b128 v[30:33], v89
	s_waitcnt lgkmcnt(4)
	v_mfma_f32_32x32x16_bf16 v[2:17], v[122:125], v[126:129], v[2:17]
	ds_read_b128 v[122:125], v89 offset:16384
	ds_read_b128 v[126:129], v1 offset:9280
	s_waitcnt lgkmcnt(4)
	v_mfma_f32_32x32x16_bf16 v[106:121], v[18:21], v[22:25], v[106:121]
	ds_read_b128 v[18:21], v1 offset:96
	ds_read_b128 v[22:25], v90
	s_waitcnt lgkmcnt(4)
	v_mfma_f32_32x32x16_bf16 v[2:17], v[26:29], v[30:33], v[2:17]
	ds_read_b128 v[26:29], v90 offset:16384
	ds_read_b128 v[30:33], v1 offset:9312
	s_waitcnt lgkmcnt(4)
	v_mfma_f32_32x32x16_bf16 v[106:121], v[122:125], v[126:129], v[106:121]
	s_waitcnt lgkmcnt(2)
	v_mfma_f32_32x32x16_bf16 v[2:17], v[18:21], v[22:25], v[2:17]
	s_waitcnt lgkmcnt(0)
	v_mfma_f32_32x32x16_bf16 v[106:121], v[26:29], v[30:33], v[106:121]
	v_or_b32_e32 v1, s34, v92
	v_lshlrev_b32_e32 v1, 1, v1
	v_add_u32_e32 v88, s7, v1
	s_add_i32 s7, s51, 0xe400
	v_add_u32_e32 v89, s7, v1
	s_lshl_b32 s7, s48, 9
	s_and_b32 s7, s7, 0x7ffffc00
	s_lshl_b32 s6, s52, 12
	s_add_i32 s6, s6, s7
	v_or_b32_e32 v1, s6, v92
	v_lshlrev_b32_e32 v1, 1, v1
	v_readlane_b32 s6, v250, 18
	s_nop 1
	v_cvt_pk_bf16_f32 v18, v2, v3
	v_cvt_pk_bf16_f32 v19, v4, v5
	v_cvt_pk_bf16_f32 v20, v6, v7
	v_cvt_pk_bf16_f32 v21, v8, v9
	buffer_store_dwordx4 v[18:21], v88, s[72:75], 0 offen sc1
	v_cvt_pk_bf16_f32 v22, v10, v11
	v_cvt_pk_bf16_f32 v23, v12, v13
	v_cvt_pk_bf16_f32 v24, v14, v15
	v_cvt_pk_bf16_f32 v25, v16, v17
	buffer_store_dwordx4 v[22:25], v89, s[72:75], 0 offen sc1
	v_add_u32_e32 v90, s51, v1
	s_addk_i32 s51, 0x400
	v_add_u32_e32 v91, s51, v1
	v_cvt_pk_bf16_f32 v26, v106, v107
	v_cvt_pk_bf16_f32 v27, v108, v109
	v_cvt_pk_bf16_f32 v28, v110, v111
	v_cvt_pk_bf16_f32 v29, v112, v113
	s_cmp_eq_u32 s50, s6
	buffer_store_dwordx4 v[26:29], v90, s[72:75], 0 offen sc1
	v_cvt_pk_bf16_f32 v30, v114, v115
	v_cvt_pk_bf16_f32 v31, v116, v117
	v_cvt_pk_bf16_f32 v32, v118, v119
	v_cvt_pk_bf16_f32 v33, v120, v121
	s_cselect_b64 s[28:29], -1, 0
	s_cmp_lg_u32 s50, s6
	buffer_store_dwordx4 v[30:33], v91, s[72:75], 0 offen sc1
	s_cbranch_scc1 .LBB0_241
	s_waitcnt vmcnt(0)
	s_and_b64 s[40:41], s[54:55], exec
